# phase_mod: b_ada pointer and bias load hoisted out of the barrier-bounded per-unit reduction (issued at unit start)
# speedup vs baseline: 1.0084x; 1.0041x over previous
; #define LAS __attribute__((address_space(3)))
; DI int TID() { int t = __builtin_amdgcn_workitem_id_x(); asm volatile("" : "+v"(t)); return t; }
; DI int GDIM() { return (int)__ockl_get_num_groups(0); }
; DI int BID() { int t = __builtin_amdgcn_workgroup_id_x(); asm volatile("" : "+s"(t)); return t; }
; DI void phase_mod(LAS unsigned char* lds, PP p) {
;     LAS float* red = (LAS float*)lds;
;     const int tid = TID(), col = tid & 31, kp = tid >> 5;
;     const float* c = p->in[1];
;     float* mod = (float*)(p->ws + O_MOD);
;     for (int u = BID(); u < 768; u += GDIM()) {
;         const int l = u / 384, c0 = (u % 384) * 32;
;         const float* w = p->in[2] + (size_t)l * 2048 * 12288 + c0 + col;
;         float s = 0.f;
;         for (int k = kp * 128; k < kp * 128 + 128; ++k) { const float cv = c[k]; s += (cv / (1.f + __expf(-cv))) * w[(size_t)k * 12288]; }
.LBB0_1262:
	s_andn2_b64 vcc, exec, s[28:29]
	s_cbranch_vccnz .LBB0_1386
	v_mov_b32_e32 v2, v201
	s_mov_b32 s20, s64
	s_cmpk_gt_i32 s20, 0x2ff
	s_cbranch_scc1 .LBB0_1270
	s_waitcnt lgkmcnt(0)
	s_load_dwordx4 s[24:27], s[0:1], 0x8
	v_lshlrev_b32_e32 v0, 2, v2
	s_waitcnt vmcnt(0)
	v_and_b32_e32 v4, 0xffffff80, v0
	s_mov_b32 s2, 0xc000
	v_and_b32_e32 v6, 31, v2
	v_add_u32_e32 v10, 0, v0
	v_mad_i64_i32 v[0:1], s[2:3], v4, s2, 0
	v_lshl_or_b32 v0, v6, 2, v0
	v_cmp_gt_i32_e64 s[22:23], 32, v2
	v_lshlrev_b32_e32 v32, 4, v2
	s_waitcnt lgkmcnt(0)
	v_lshl_add_u64 v[0:1], s[26:27], 0, v[0:1]
	global_load_dwordx4 v[28:31], v32, s[24:25]
	v_and_b32_e32 v33, 0xfffffe00, v32
	s_mov_b64 s[26:27], 0xc000
	s_waitcnt vmcnt(0)
	v_mul_f32_e32 v17, 0xbfb8aa3b, v28
	v_exp_f32_e32 v17, v17
	s_nop 0
	v_add_f32_e32 v17, 1.0, v17
	v_rcp_f32_e32 v19, v17
	s_nop 0
	v_mul_f32_e32 v21, v28, v19
	v_fma_f32 v22, -v17, v21, v28
	v_fmac_f32_e32 v21, v22, v19
	v_div_fixup_f32 v28, v21, v17, v28
	v_mul_f32_e32 v17, 0xbfb8aa3b, v29
	v_exp_f32_e32 v17, v17
	s_nop 0
	v_add_f32_e32 v17, 1.0, v17
	v_rcp_f32_e32 v19, v17
	s_nop 0
	v_mul_f32_e32 v21, v29, v19
	v_fma_f32 v22, -v17, v21, v29
	v_fmac_f32_e32 v21, v22, v19
	v_div_fixup_f32 v29, v21, v17, v29
	v_mul_f32_e32 v17, 0xbfb8aa3b, v30
	v_exp_f32_e32 v17, v17
	s_nop 0
	v_add_f32_e32 v17, 1.0, v17
	v_rcp_f32_e32 v19, v17
	s_nop 0
	v_mul_f32_e32 v21, v30, v19
	v_fma_f32 v22, -v17, v21, v30
	v_fmac_f32_e32 v21, v22, v19
	v_div_fixup_f32 v30, v21, v17, v30
	v_mul_f32_e32 v17, 0xbfb8aa3b, v31
	v_exp_f32_e32 v17, v17
	s_nop 0
	v_add_f32_e32 v17, 1.0, v17
	v_rcp_f32_e32 v19, v17
	s_nop 0
	v_mul_f32_e32 v21, v31, v19
	v_fma_f32 v22, -v17, v21, v31
	v_fmac_f32_e32 v21, v22, v19
	v_div_fixup_f32 v31, v21, v17, v31
	ds_write_b128 v32, v[28:31] offset:4096
	s_load_dwordx2 s[28:29], s[0:1], 0x18
	s_waitcnt lgkmcnt(0)
	s_barrier
	s_branch .LBB0_1266

; DI int GDIM() { return (int)__ockl_get_num_groups(0); }
; DI int BID() { int t = __builtin_amdgcn_workgroup_id_x(); asm volatile("" : "+s"(t)); return t; }
; DI void phase_mod(LAS unsigned char* lds, PP p) {
;     ...
;     for (int u = BID(); u < 768; u += GDIM()) {
;         const int l = u / 384, c0 = (u % 384) * 32;
;         const float* w = p->in[2] + (size_t)l * 2048 * 12288 + c0 + col;
;         float s = 0.f;
;         for (int k = kp * 128; k < kp * 128 + 128; ++k) { const float cv = c[k]; s += (cv / (1.f + __expf(-cv))) * w[(size_t)k * 12288]; }
.LBB0_1266:
	s_mul_hi_i32 s2, s20, 0x2aaaaaab
	s_lshr_b32 s3, s2, 31
	s_ashr_i32 s21, s2, 6
	s_add_i32 s21, s21, s3
	s_mul_i32 s2, s21, 0x180
	s_sub_i32 s2, s20, s2
	s_lshl_b32 s2, s2, 5
	s_ashr_i32 s3, s2, 31
	s_mul_i32 s25, s21, 0x6000000
	s_lshl_b64 s[4:5], s[2:3], 2
	s_mul_hi_i32 s24, s21, 0x6000000
	s_add_u32 s4, s25, s4
	s_addc_u32 s5, s24, s5
	v_lshl_add_u64 v[6:7], v[0:1], 0, s[4:5]
	v_mov_b32_e32 v13, 0
	s_mul_i32 s3, s21, 0x3000
	s_add_i32 s3, s3, s2
	v_add_lshl_u32 v105, s3, v2, 2
	s_and_saveexec_b64 s[30:31], s[22:23]
	s_cbranch_execz .Lmod_nobias
	global_load_dword v104, v105, s[28:29]
.Lmod_nobias:
	s_mov_b64 exec, s[30:31]
	global_load_dword v40, v[6:7], off
	v_lshl_add_u64 v[6:7], v[6:7], 0, s[26:27]
	global_load_dword v41, v[6:7], off
	v_lshl_add_u64 v[6:7], v[6:7], 0, s[26:27]
	global_load_dword v42, v[6:7], off
	v_lshl_add_u64 v[6:7], v[6:7], 0, s[26:27]
	global_load_dword v43, v[6:7], off
	v_lshl_add_u64 v[6:7], v[6:7], 0, s[26:27]
	global_load_dword v44, v[6:7], off
	v_lshl_add_u64 v[6:7], v[6:7], 0, s[26:27]
	global_load_dword v45, v[6:7], off
	v_lshl_add_u64 v[6:7], v[6:7], 0, s[26:27]
	global_load_dword v46, v[6:7], off
	v_lshl_add_u64 v[6:7], v[6:7], 0, s[26:27]
	global_load_dword v47, v[6:7], off
	v_lshl_add_u64 v[6:7], v[6:7], 0, s[26:27]
	global_load_dword v48, v[6:7], off
	v_lshl_add_u64 v[6:7], v[6:7], 0, s[26:27]
	global_load_dword v49, v[6:7], off
	v_lshl_add_u64 v[6:7], v[6:7], 0, s[26:27]
	global_load_dword v50, v[6:7], off
	v_lshl_add_u64 v[6:7], v[6:7], 0, s[26:27]
	global_load_dword v51, v[6:7], off
	v_lshl_add_u64 v[6:7], v[6:7], 0, s[26:27]
	global_load_dword v52, v[6:7], off
	v_lshl_add_u64 v[6:7], v[6:7], 0, s[26:27]
	global_load_dword v53, v[6:7], off
	v_lshl_add_u64 v[6:7], v[6:7], 0, s[26:27]
	global_load_dword v54, v[6:7], off
	v_lshl_add_u64 v[6:7], v[6:7], 0, s[26:27]
	global_load_dword v55, v[6:7], off
	v_lshl_add_u64 v[6:7], v[6:7], 0, s[26:27]
	global_load_dword v56, v[6:7], off
	v_lshl_add_u64 v[6:7], v[6:7], 0, s[26:27]
	global_load_dword v57, v[6:7], off
	v_lshl_add_u64 v[6:7], v[6:7], 0, s[26:27]
	global_load_dword v58, v[6:7], off
	v_lshl_add_u64 v[6:7], v[6:7], 0, s[26:27]
	global_load_dword v59, v[6:7], off
	v_lshl_add_u64 v[6:7], v[6:7], 0, s[26:27]
	global_load_dword v60, v[6:7], off
	v_lshl_add_u64 v[6:7], v[6:7], 0, s[26:27]
	global_load_dword v61, v[6:7], off
	v_lshl_add_u64 v[6:7], v[6:7], 0, s[26:27]
	global_load_dword v62, v[6:7], off
	v_lshl_add_u64 v[6:7], v[6:7], 0, s[26:27]
	global_load_dword v63, v[6:7], off
	v_lshl_add_u64 v[6:7], v[6:7], 0, s[26:27]
	global_load_dword v64, v[6:7], off
	v_lshl_add_u64 v[6:7], v[6:7], 0, s[26:27]
	global_load_dword v65, v[6:7], off
	v_lshl_add_u64 v[6:7], v[6:7], 0, s[26:27]
	global_load_dword v66, v[6:7], off
	v_lshl_add_u64 v[6:7], v[6:7], 0, s[26:27]
	global_load_dword v67, v[6:7], off
	v_lshl_add_u64 v[6:7], v[6:7], 0, s[26:27]
	global_load_dword v68, v[6:7], off
	v_lshl_add_u64 v[6:7], v[6:7], 0, s[26:27]
	global_load_dword v69, v[6:7], off
	v_lshl_add_u64 v[6:7], v[6:7], 0, s[26:27]
	global_load_dword v70, v[6:7], off
	v_lshl_add_u64 v[6:7], v[6:7], 0, s[26:27]
	global_load_dword v71, v[6:7], off
	v_lshl_add_u64 v[6:7], v[6:7], 0, s[26:27]
	global_load_dword v72, v[6:7], off
	v_lshl_add_u64 v[6:7], v[6:7], 0, s[26:27]
	global_load_dword v73, v[6:7], off
	v_lshl_add_u64 v[6:7], v[6:7], 0, s[26:27]
	global_load_dword v74, v[6:7], off
	v_lshl_add_u64 v[6:7], v[6:7], 0, s[26:27]
	global_load_dword v75, v[6:7], off
	v_lshl_add_u64 v[6:7], v[6:7], 0, s[26:27]
	global_load_dword v76, v[6:7], off
	v_lshl_add_u64 v[6:7], v[6:7], 0, s[26:27]
	global_load_dword v77, v[6:7], off
	v_lshl_add_u64 v[6:7], v[6:7], 0, s[26:27]
	global_load_dword v78, v[6:7], off
	v_lshl_add_u64 v[6:7], v[6:7], 0, s[26:27]
	global_load_dword v79, v[6:7], off
	v_lshl_add_u64 v[6:7], v[6:7], 0, s[26:27]
	global_load_dword v80, v[6:7], off
	v_lshl_add_u64 v[6:7], v[6:7], 0, s[26:27]
	global_load_dword v81, v[6:7], off
	v_lshl_add_u64 v[6:7], v[6:7], 0, s[26:27]
	global_load_dword v82, v[6:7], off
	v_lshl_add_u64 v[6:7], v[6:7], 0, s[26:27]
	global_load_dword v83, v[6:7], off
	v_lshl_add_u64 v[6:7], v[6:7], 0, s[26:27]
	global_load_dword v84, v[6:7], off
	v_lshl_add_u64 v[6:7], v[6:7], 0, s[26:27]
	global_load_dword v85, v[6:7], off
	v_lshl_add_u64 v[6:7], v[6:7], 0, s[26:27]
	global_load_dword v86, v[6:7], off
	v_lshl_add_u64 v[6:7], v[6:7], 0, s[26:27]
	global_load_dword v87, v[6:7], off
	v_lshl_add_u64 v[6:7], v[6:7], 0, s[26:27]
	ds_read_b128 v[88:91], v33 offset:4096
	ds_read_b128 v[92:95], v33 offset:4112
	ds_read_b128 v[96:99], v33 offset:4128
	ds_read_b128 v[100:103], v33 offset:4144
	s_waitcnt vmcnt(32)
	s_waitcnt lgkmcnt(0)
; DI void phase_mod(LAS unsigned char* lds, PP p) {
;     ...
;         for (int k = kp * 128; k < kp * 128 + 128; ++k) { const float cv = c[k]; s += (cv / (1.f + __expf(-cv))) * w[(size_t)k * 12288]; }
	v_fmac_f32_e32 v13, v40, v88
	v_fmac_f32_e32 v13, v41, v89
	v_fmac_f32_e32 v13, v42, v90
	v_fmac_f32_e32 v13, v43, v91
	v_fmac_f32_e32 v13, v44, v92
	v_fmac_f32_e32 v13, v45, v93
	v_fmac_f32_e32 v13, v46, v94
	v_fmac_f32_e32 v13, v47, v95
	v_fmac_f32_e32 v13, v48, v96
	v_fmac_f32_e32 v13, v49, v97
	v_fmac_f32_e32 v13, v50, v98
	v_fmac_f32_e32 v13, v51, v99
	v_fmac_f32_e32 v13, v52, v100
	v_fmac_f32_e32 v13, v53, v101
	v_fmac_f32_e32 v13, v54, v102
	v_fmac_f32_e32 v13, v55, v103
	global_load_dword v40, v[6:7], off
	v_lshl_add_u64 v[6:7], v[6:7], 0, s[26:27]
	global_load_dword v41, v[6:7], off
	v_lshl_add_u64 v[6:7], v[6:7], 0, s[26:27]
	global_load_dword v42, v[6:7], off
	v_lshl_add_u64 v[6:7], v[6:7], 0, s[26:27]
	global_load_dword v43, v[6:7], off
	v_lshl_add_u64 v[6:7], v[6:7], 0, s[26:27]
	global_load_dword v44, v[6:7], off
	v_lshl_add_u64 v[6:7], v[6:7], 0, s[26:27]
	global_load_dword v45, v[6:7], off
	v_lshl_add_u64 v[6:7], v[6:7], 0, s[26:27]
	global_load_dword v46, v[6:7], off
	v_lshl_add_u64 v[6:7], v[6:7], 0, s[26:27]
	global_load_dword v47, v[6:7], off
	v_lshl_add_u64 v[6:7], v[6:7], 0, s[26:27]
	global_load_dword v48, v[6:7], off
	v_lshl_add_u64 v[6:7], v[6:7], 0, s[26:27]
	global_load_dword v49, v[6:7], off
	v_lshl_add_u64 v[6:7], v[6:7], 0, s[26:27]
	global_load_dword v50, v[6:7], off
	v_lshl_add_u64 v[6:7], v[6:7], 0, s[26:27]
	global_load_dword v51, v[6:7], off
	v_lshl_add_u64 v[6:7], v[6:7], 0, s[26:27]
	global_load_dword v52, v[6:7], off
	v_lshl_add_u64 v[6:7], v[6:7], 0, s[26:27]
	global_load_dword v53, v[6:7], off
	v_lshl_add_u64 v[6:7], v[6:7], 0, s[26:27]
	global_load_dword v54, v[6:7], off
	v_lshl_add_u64 v[6:7], v[6:7], 0, s[26:27]
	global_load_dword v55, v[6:7], off
	v_lshl_add_u64 v[6:7], v[6:7], 0, s[26:27]
	ds_read_b128 v[88:91], v33 offset:4160
	ds_read_b128 v[92:95], v33 offset:4176
	ds_read_b128 v[96:99], v33 offset:4192
	ds_read_b128 v[100:103], v33 offset:4208
	s_waitcnt vmcnt(32)
	s_waitcnt lgkmcnt(0)
	v_fmac_f32_e32 v13, v56, v88
	v_fmac_f32_e32 v13, v57, v89
	v_fmac_f32_e32 v13, v58, v90
	v_fmac_f32_e32 v13, v59, v91
	v_fmac_f32_e32 v13, v60, v92
	v_fmac_f32_e32 v13, v61, v93
	v_fmac_f32_e32 v13, v62, v94
	v_fmac_f32_e32 v13, v63, v95
	v_fmac_f32_e32 v13, v64, v96
	v_fmac_f32_e32 v13, v65, v97
	v_fmac_f32_e32 v13, v66, v98
	v_fmac_f32_e32 v13, v67, v99
	v_fmac_f32_e32 v13, v68, v100
	v_fmac_f32_e32 v13, v69, v101
	v_fmac_f32_e32 v13, v70, v102
	v_fmac_f32_e32 v13, v71, v103
	global_load_dword v56, v[6:7], off
	v_lshl_add_u64 v[6:7], v[6:7], 0, s[26:27]
	global_load_dword v57, v[6:7], off
	v_lshl_add_u64 v[6:7], v[6:7], 0, s[26:27]
	global_load_dword v58, v[6:7], off
	v_lshl_add_u64 v[6:7], v[6:7], 0, s[26:27]
	global_load_dword v59, v[6:7], off
	v_lshl_add_u64 v[6:7], v[6:7], 0, s[26:27]
	global_load_dword v60, v[6:7], off
	v_lshl_add_u64 v[6:7], v[6:7], 0, s[26:27]
	global_load_dword v61, v[6:7], off
	v_lshl_add_u64 v[6:7], v[6:7], 0, s[26:27]
	global_load_dword v62, v[6:7], off
	v_lshl_add_u64 v[6:7], v[6:7], 0, s[26:27]
	global_load_dword v63, v[6:7], off
	v_lshl_add_u64 v[6:7], v[6:7], 0, s[26:27]
	global_load_dword v64, v[6:7], off
	v_lshl_add_u64 v[6:7], v[6:7], 0, s[26:27]
	global_load_dword v65, v[6:7], off
	v_lshl_add_u64 v[6:7], v[6:7], 0, s[26:27]
	global_load_dword v66, v[6:7], off
	v_lshl_add_u64 v[6:7], v[6:7], 0, s[26:27]
	global_load_dword v67, v[6:7], off
	v_lshl_add_u64 v[6:7], v[6:7], 0, s[26:27]
	global_load_dword v68, v[6:7], off
	v_lshl_add_u64 v[6:7], v[6:7], 0, s[26:27]
	global_load_dword v69, v[6:7], off
	v_lshl_add_u64 v[6:7], v[6:7], 0, s[26:27]
	global_load_dword v70, v[6:7], off
	v_lshl_add_u64 v[6:7], v[6:7], 0, s[26:27]
	global_load_dword v71, v[6:7], off
	v_lshl_add_u64 v[6:7], v[6:7], 0, s[26:27]
	ds_read_b128 v[88:91], v33 offset:4224
	ds_read_b128 v[92:95], v33 offset:4240
	ds_read_b128 v[96:99], v33 offset:4256
	ds_read_b128 v[100:103], v33 offset:4272
	s_waitcnt vmcnt(32)
	s_waitcnt lgkmcnt(0)
	v_fmac_f32_e32 v13, v72, v88
	v_fmac_f32_e32 v13, v73, v89
	v_fmac_f32_e32 v13, v74, v90
	v_fmac_f32_e32 v13, v75, v91
	v_fmac_f32_e32 v13, v76, v92
	v_fmac_f32_e32 v13, v77, v93
	v_fmac_f32_e32 v13, v78, v94
	v_fmac_f32_e32 v13, v79, v95
	v_fmac_f32_e32 v13, v80, v96
	v_fmac_f32_e32 v13, v81, v97
	v_fmac_f32_e32 v13, v82, v98
	v_fmac_f32_e32 v13, v83, v99
	v_fmac_f32_e32 v13, v84, v100
	v_fmac_f32_e32 v13, v85, v101
	v_fmac_f32_e32 v13, v86, v102
	v_fmac_f32_e32 v13, v87, v103
	global_load_dword v72, v[6:7], off
	v_lshl_add_u64 v[6:7], v[6:7], 0, s[26:27]
	global_load_dword v73, v[6:7], off
	v_lshl_add_u64 v[6:7], v[6:7], 0, s[26:27]
	global_load_dword v74, v[6:7], off
	v_lshl_add_u64 v[6:7], v[6:7], 0, s[26:27]
	global_load_dword v75, v[6:7], off
	v_lshl_add_u64 v[6:7], v[6:7], 0, s[26:27]
	global_load_dword v76, v[6:7], off
	v_lshl_add_u64 v[6:7], v[6:7], 0, s[26:27]
	global_load_dword v77, v[6:7], off
	v_lshl_add_u64 v[6:7], v[6:7], 0, s[26:27]
	global_load_dword v78, v[6:7], off
	v_lshl_add_u64 v[6:7], v[6:7], 0, s[26:27]
	global_load_dword v79, v[6:7], off
	v_lshl_add_u64 v[6:7], v[6:7], 0, s[26:27]
	global_load_dword v80, v[6:7], off
	v_lshl_add_u64 v[6:7], v[6:7], 0, s[26:27]
	global_load_dword v81, v[6:7], off
	v_lshl_add_u64 v[6:7], v[6:7], 0, s[26:27]
	global_load_dword v82, v[6:7], off
	v_lshl_add_u64 v[6:7], v[6:7], 0, s[26:27]
	global_load_dword v83, v[6:7], off
	v_lshl_add_u64 v[6:7], v[6:7], 0, s[26:27]
	global_load_dword v84, v[6:7], off
	v_lshl_add_u64 v[6:7], v[6:7], 0, s[26:27]
	global_load_dword v85, v[6:7], off
	v_lshl_add_u64 v[6:7], v[6:7], 0, s[26:27]
	global_load_dword v86, v[6:7], off
	v_lshl_add_u64 v[6:7], v[6:7], 0, s[26:27]
	global_load_dword v87, v[6:7], off
	v_lshl_add_u64 v[6:7], v[6:7], 0, s[26:27]
	ds_read_b128 v[88:91], v33 offset:4288
	ds_read_b128 v[92:95], v33 offset:4304
	ds_read_b128 v[96:99], v33 offset:4320
	ds_read_b128 v[100:103], v33 offset:4336
	s_waitcnt vmcnt(32)
; DI void phase_mod(LAS unsigned char* lds, PP p) {
;     ...
;         for (int k = kp * 128; k < kp * 128 + 128; ++k) { const float cv = c[k]; s += (cv / (1.f + __expf(-cv))) * w[(size_t)k * 12288]; }
;         red[kp * 32 + col] = s;
;         __syncthreads();
	s_waitcnt lgkmcnt(0)
	v_fmac_f32_e32 v13, v40, v88
	v_fmac_f32_e32 v13, v41, v89
	v_fmac_f32_e32 v13, v42, v90
	v_fmac_f32_e32 v13, v43, v91
	v_fmac_f32_e32 v13, v44, v92
	v_fmac_f32_e32 v13, v45, v93
	v_fmac_f32_e32 v13, v46, v94
	v_fmac_f32_e32 v13, v47, v95
	v_fmac_f32_e32 v13, v48, v96
	v_fmac_f32_e32 v13, v49, v97
	v_fmac_f32_e32 v13, v50, v98
	v_fmac_f32_e32 v13, v51, v99
	v_fmac_f32_e32 v13, v52, v100
	v_fmac_f32_e32 v13, v53, v101
	v_fmac_f32_e32 v13, v54, v102
	v_fmac_f32_e32 v13, v55, v103
	global_load_dword v40, v[6:7], off
	v_lshl_add_u64 v[6:7], v[6:7], 0, s[26:27]
	global_load_dword v41, v[6:7], off
	v_lshl_add_u64 v[6:7], v[6:7], 0, s[26:27]
	global_load_dword v42, v[6:7], off
	v_lshl_add_u64 v[6:7], v[6:7], 0, s[26:27]
	global_load_dword v43, v[6:7], off
	v_lshl_add_u64 v[6:7], v[6:7], 0, s[26:27]
	global_load_dword v44, v[6:7], off
	v_lshl_add_u64 v[6:7], v[6:7], 0, s[26:27]
	global_load_dword v45, v[6:7], off
	v_lshl_add_u64 v[6:7], v[6:7], 0, s[26:27]
	global_load_dword v46, v[6:7], off
	v_lshl_add_u64 v[6:7], v[6:7], 0, s[26:27]
	global_load_dword v47, v[6:7], off
	v_lshl_add_u64 v[6:7], v[6:7], 0, s[26:27]
	global_load_dword v48, v[6:7], off
	v_lshl_add_u64 v[6:7], v[6:7], 0, s[26:27]
	global_load_dword v49, v[6:7], off
	v_lshl_add_u64 v[6:7], v[6:7], 0, s[26:27]
	global_load_dword v50, v[6:7], off
	v_lshl_add_u64 v[6:7], v[6:7], 0, s[26:27]
	global_load_dword v51, v[6:7], off
	v_lshl_add_u64 v[6:7], v[6:7], 0, s[26:27]
	global_load_dword v52, v[6:7], off
	v_lshl_add_u64 v[6:7], v[6:7], 0, s[26:27]
	global_load_dword v53, v[6:7], off
	v_lshl_add_u64 v[6:7], v[6:7], 0, s[26:27]
	global_load_dword v54, v[6:7], off
	v_lshl_add_u64 v[6:7], v[6:7], 0, s[26:27]
	global_load_dword v55, v[6:7], off
	v_lshl_add_u64 v[6:7], v[6:7], 0, s[26:27]
	ds_read_b128 v[88:91], v33 offset:4352
	ds_read_b128 v[92:95], v33 offset:4368
	ds_read_b128 v[96:99], v33 offset:4384
	ds_read_b128 v[100:103], v33 offset:4400
	s_waitcnt vmcnt(32)
	s_waitcnt lgkmcnt(0)
	v_fmac_f32_e32 v13, v56, v88
	v_fmac_f32_e32 v13, v57, v89
	v_fmac_f32_e32 v13, v58, v90
	v_fmac_f32_e32 v13, v59, v91
	v_fmac_f32_e32 v13, v60, v92
	v_fmac_f32_e32 v13, v61, v93
	v_fmac_f32_e32 v13, v62, v94
	v_fmac_f32_e32 v13, v63, v95
	v_fmac_f32_e32 v13, v64, v96
	v_fmac_f32_e32 v13, v65, v97
	v_fmac_f32_e32 v13, v66, v98
	v_fmac_f32_e32 v13, v67, v99
	v_fmac_f32_e32 v13, v68, v100
	v_fmac_f32_e32 v13, v69, v101
	v_fmac_f32_e32 v13, v70, v102
	v_fmac_f32_e32 v13, v71, v103
	global_load_dword v56, v[6:7], off
	v_lshl_add_u64 v[6:7], v[6:7], 0, s[26:27]
	global_load_dword v57, v[6:7], off
	v_lshl_add_u64 v[6:7], v[6:7], 0, s[26:27]
	global_load_dword v58, v[6:7], off
	v_lshl_add_u64 v[6:7], v[6:7], 0, s[26:27]
	global_load_dword v59, v[6:7], off
	v_lshl_add_u64 v[6:7], v[6:7], 0, s[26:27]
	global_load_dword v60, v[6:7], off
	v_lshl_add_u64 v[6:7], v[6:7], 0, s[26:27]
	global_load_dword v61, v[6:7], off
	v_lshl_add_u64 v[6:7], v[6:7], 0, s[26:27]
	global_load_dword v62, v[6:7], off
	v_lshl_add_u64 v[6:7], v[6:7], 0, s[26:27]
	global_load_dword v63, v[6:7], off
	v_lshl_add_u64 v[6:7], v[6:7], 0, s[26:27]
	global_load_dword v64, v[6:7], off
	v_lshl_add_u64 v[6:7], v[6:7], 0, s[26:27]
	global_load_dword v65, v[6:7], off
	v_lshl_add_u64 v[6:7], v[6:7], 0, s[26:27]
	global_load_dword v66, v[6:7], off
	v_lshl_add_u64 v[6:7], v[6:7], 0, s[26:27]
	global_load_dword v67, v[6:7], off
	v_lshl_add_u64 v[6:7], v[6:7], 0, s[26:27]
	global_load_dword v68, v[6:7], off
	v_lshl_add_u64 v[6:7], v[6:7], 0, s[26:27]
	global_load_dword v69, v[6:7], off
	v_lshl_add_u64 v[6:7], v[6:7], 0, s[26:27]
	global_load_dword v70, v[6:7], off
	v_lshl_add_u64 v[6:7], v[6:7], 0, s[26:27]
	global_load_dword v71, v[6:7], off
	ds_read_b128 v[88:91], v33 offset:4416
	ds_read_b128 v[92:95], v33 offset:4432
	ds_read_b128 v[96:99], v33 offset:4448
	ds_read_b128 v[100:103], v33 offset:4464
	s_waitcnt vmcnt(32)
	s_waitcnt lgkmcnt(0)
	v_fmac_f32_e32 v13, v72, v88
	v_fmac_f32_e32 v13, v73, v89
	v_fmac_f32_e32 v13, v74, v90
	v_fmac_f32_e32 v13, v75, v91
	v_fmac_f32_e32 v13, v76, v92
	v_fmac_f32_e32 v13, v77, v93
	v_fmac_f32_e32 v13, v78, v94
	v_fmac_f32_e32 v13, v79, v95
	v_fmac_f32_e32 v13, v80, v96
	v_fmac_f32_e32 v13, v81, v97
	v_fmac_f32_e32 v13, v82, v98
	v_fmac_f32_e32 v13, v83, v99
	v_fmac_f32_e32 v13, v84, v100
	v_fmac_f32_e32 v13, v85, v101
	v_fmac_f32_e32 v13, v86, v102
	v_fmac_f32_e32 v13, v87, v103
	ds_read_b128 v[88:91], v33 offset:4480
	ds_read_b128 v[92:95], v33 offset:4496
	ds_read_b128 v[96:99], v33 offset:4512
	ds_read_b128 v[100:103], v33 offset:4528
	s_waitcnt vmcnt(16)
	s_waitcnt lgkmcnt(0)
	v_fmac_f32_e32 v13, v40, v88
	v_fmac_f32_e32 v13, v41, v89
	v_fmac_f32_e32 v13, v42, v90
	v_fmac_f32_e32 v13, v43, v91
	v_fmac_f32_e32 v13, v44, v92
	v_fmac_f32_e32 v13, v45, v93
	v_fmac_f32_e32 v13, v46, v94
	v_fmac_f32_e32 v13, v47, v95
	v_fmac_f32_e32 v13, v48, v96
	v_fmac_f32_e32 v13, v49, v97
	v_fmac_f32_e32 v13, v50, v98
	v_fmac_f32_e32 v13, v51, v99
	v_fmac_f32_e32 v13, v52, v100
	v_fmac_f32_e32 v13, v53, v101
	v_fmac_f32_e32 v13, v54, v102
	v_fmac_f32_e32 v13, v55, v103
	ds_read_b128 v[88:91], v33 offset:4544
	ds_read_b128 v[92:95], v33 offset:4560
	ds_read_b128 v[96:99], v33 offset:4576
	ds_read_b128 v[100:103], v33 offset:4592
	s_waitcnt vmcnt(0)
	s_waitcnt lgkmcnt(0)
	v_fmac_f32_e32 v13, v56, v88
	v_fmac_f32_e32 v13, v57, v89
	v_fmac_f32_e32 v13, v58, v90
	v_fmac_f32_e32 v13, v59, v91
	v_fmac_f32_e32 v13, v60, v92
	v_fmac_f32_e32 v13, v61, v93
	v_fmac_f32_e32 v13, v62, v94
	v_fmac_f32_e32 v13, v63, v95
	v_fmac_f32_e32 v13, v64, v96
	v_fmac_f32_e32 v13, v65, v97
	v_fmac_f32_e32 v13, v66, v98
	v_fmac_f32_e32 v13, v67, v99
	v_fmac_f32_e32 v13, v68, v100
	v_fmac_f32_e32 v13, v69, v101
	v_fmac_f32_e32 v13, v70, v102
	v_fmac_f32_e32 v13, v71, v103
	ds_write_b32 v10, v13
	s_waitcnt lgkmcnt(0)
	s_barrier
; DI void phase_mod(LAS unsigned char* lds, PP p) {
;     ...
;         if (tid < 32) { float t = 0.f; for (int i = 0; i < 16; ++i) t += red[i * 32 + tid]; mod[l * 12288 + c0 + tid] = t + p->in[3][l * 12288 + c0 + tid]; }
	s_and_saveexec_b64 s[4:5], s[22:23]
	s_cbranch_execz .LBB0_1265
	s_mul_i32 s3, s21, 0x3000
	s_add_i32 s3, s3, s2
	v_add_u32_e32 v6, s3, v2
	v_ashrrev_i32_e32 v7, 31, v6
	v_lshlrev_b64 v[6:7], 2, v[6:7]
	ds_read2_b32 v[8:9], v10 offset1:32
	ds_read2_b32 v[14:15], v10 offset0:64 offset1:96
	ds_read2_b32 v[16:17], v10 offset0:128 offset1:160
	ds_read2_b32 v[18:19], v10 offset0:192 offset1:224
	v_add_u32_e32 v26, 0x400, v10
	s_waitcnt lgkmcnt(3)
	v_add_f32_e32 v8, 0, v8
	v_add_f32_e32 v8, v8, v9
	s_waitcnt lgkmcnt(2)
	v_add_f32_e32 v8, v8, v14
	v_add_f32_e32 v8, v8, v15
	s_waitcnt lgkmcnt(1)
	v_add_f32_e32 v8, v8, v16
	v_add_f32_e32 v8, v8, v17
	ds_read2_b32 v[20:21], v26 offset1:32
	ds_read2_b32 v[22:23], v26 offset0:64 offset1:96
	ds_read2_b32 v[24:25], v26 offset0:128 offset1:160
	ds_read2_b32 v[26:27], v26 offset0:192 offset1:224
	s_waitcnt lgkmcnt(4)
	v_add_f32_e32 v8, v8, v18
	v_add_f32_e32 v8, v8, v19
	s_waitcnt lgkmcnt(3)
	v_add_f32_e32 v8, v8, v20
	v_add_f32_e32 v8, v8, v21
	s_waitcnt lgkmcnt(2)
	v_add_f32_e32 v8, v8, v22
	v_add_f32_e32 v8, v8, v23
	s_waitcnt lgkmcnt(1)
	v_add_f32_e32 v8, v8, v24
	v_add_f32_e32 v8, v8, v25
	s_waitcnt lgkmcnt(0)
	v_add_f32_e32 v8, v8, v26
	v_add_f32_e32 v8, v8, v27
	v_lshl_add_u64 v[6:7], s[46:47], 0, v[6:7]
	s_waitcnt vmcnt(0)
	v_add_f32_e32 v8, v8, v104
	global_store_dword v[6:7], v8, off
	s_branch .LBB0_1265
